# P10: Q-fragment and gate-row loads marked nt (read once) to keep K/V resident
# baseline (speedup 1.0000x reference)
.LBB0_1220:
	ds_bpermute_b32 v64, v241, v184
	s_mul_i32 s6, s50, 0x1e00
	s_add_u32 s6, s61, s6
	s_addc_u32 s7, s62, 0
	s_lshl_b32 s10, s49, 1
	s_add_u32 s6, s6, s10
	s_addc_u32 s7, s7, 0
	s_lshl_b32 s8, s50, 12
	s_waitcnt lgkmcnt(0)
	v_add_f32_e32 v72, v184, v64
	s_add_u32 s11, s63, s8
	v_div_scale_f32 v73, s[8:9], v72, v72, 1.0
	v_rcp_f32_e32 v74, v73
	s_addc_u32 s9, s64, 0
	s_add_u32 s8, s11, s10
	s_addc_u32 s9, s9, 0
	v_lshlrev_b32_e32 v144, 1, v150
	v_fma_f32 v64, -v73, v74, 1.0
	v_lshl_add_u64 v[70:71], s[6:7], 0, v[144:145]
	v_lshl_add_u64 v[68:69], s[8:9], 0, v[144:145]
	v_or_b32_e32 v144, s24, v199
	v_fmac_f32_e32 v74, v64, v74
	v_mad_u64_u32 v[64:65], s[6:7], v144, s72, v[70:71]
	s_waitcnt vmcnt(0)
	s_barrier
	global_load_dwordx4 v[64:67], v[64:65], off offset:1024 nt
	v_or_b32_e32 v95, 4, v144
	v_mad_u64_u32 v[130:131], s[6:7], v95, s72, v[70:71]
	global_load_dwordx4 v[100:103], v[130:131], off offset:1024 nt
	v_or_b32_e32 v95, 8, v144
	v_mad_u64_u32 v[132:133], s[6:7], v95, s72, v[70:71]
	global_load_dwordx4 v[104:107], v[132:133], off offset:1024 nt
	v_or_b32_e32 v95, 12, v144
	v_mad_u64_u32 v[134:135], s[6:7], v95, s72, v[70:71]
	global_load_dwordx4 v[108:111], v[134:135], off offset:1024 nt
	v_or_b32_e32 v95, 16, v144
	v_mad_u64_u32 v[136:137], s[6:7], v95, s72, v[70:71]
	global_load_dwordx4 v[112:115], v[136:137], off offset:1024 nt
	v_or_b32_e32 v95, 20, v144
	v_mad_u64_u32 v[138:139], s[6:7], v95, s72, v[70:71]
	global_load_dwordx4 v[116:119], v[138:139], off offset:1024 nt
	v_or_b32_e32 v95, 24, v144
	v_mad_u64_u32 v[140:141], s[6:7], v95, s72, v[70:71]
	global_load_dwordx4 v[120:123], v[140:141], off offset:1024 nt
	v_or_b32_e32 v95, 28, v144
	v_mad_u64_u32 v[142:143], s[6:7], v95, s72, v[70:71]
	global_load_dwordx4 v[124:127], v[142:143], off offset:1024 nt
	v_div_scale_f32 v75, vcc, 1.0, v72, 1.0
	v_mul_f32_e32 v76, v75, v74
	v_fma_f32 v77, -v73, v76, v75
	v_fmac_f32_e32 v76, v77, v74
	v_fma_f32 v73, -v73, v76, v75
	v_div_fmas_f32 v73, v73, v74, v76
	v_div_fixup_f32 v72, v73, v72, 1.0
	v_pk_mul_f32 v[16:17], v[16:17], v[72:73] op_sel_hi:[1,0]
	v_pk_mul_f32 v[18:19], v[18:19], v[72:73] op_sel_hi:[1,0]
	v_cvt_pk_bf16_f32 v16, v16, v17
	v_cvt_pk_bf16_f32 v17, v18, v19
	v_pk_mul_f32 v[18:19], v[20:21], v[72:73] op_sel_hi:[1,0]
	v_pk_mul_f32 v[20:21], v[22:23], v[72:73] op_sel_hi:[1,0]
	v_pk_mul_f32 v[0:1], v[0:1], v[72:73] op_sel_hi:[1,0]
	v_pk_mul_f32 v[2:3], v[2:3], v[72:73] op_sel_hi:[1,0]
	v_mad_u64_u32 v[74:75], s[6:7], v240, s69, v[146:147]
	v_cvt_pk_bf16_f32 v18, v18, v19
	v_cvt_pk_bf16_f32 v19, v20, v21
	v_cvt_pk_bf16_f32 v0, v0, v1
	v_cvt_pk_bf16_f32 v1, v2, v3
	v_pk_mul_f32 v[2:3], v[4:5], v[72:73] op_sel_hi:[1,0]
	v_pk_mul_f32 v[4:5], v[6:7], v[72:73] op_sel_hi:[1,0]
	ds_write2_b64 v74, v[16:17], v[18:19] offset0:16 offset1:18
	v_pk_mul_f32 v[16:17], v[24:25], v[72:73] op_sel_hi:[1,0]
	v_pk_mul_f32 v[18:19], v[26:27], v[72:73] op_sel_hi:[1,0]
	v_cvt_pk_bf16_f32 v2, v2, v3
	v_cvt_pk_bf16_f32 v3, v4, v5
	v_cvt_pk_bf16_f32 v16, v16, v17
	v_cvt_pk_bf16_f32 v17, v18, v19
	v_pk_mul_f32 v[18:19], v[28:29], v[72:73] op_sel_hi:[1,0]
	v_pk_mul_f32 v[20:21], v[30:31], v[72:73] op_sel_hi:[1,0]
	ds_write2_b64 v74, v[0:1], v[2:3] offset0:24 offset1:26
	v_pk_mul_f32 v[0:1], v[8:9], v[72:73] op_sel_hi:[1,0]
	v_pk_mul_f32 v[2:3], v[10:11], v[72:73] op_sel_hi:[1,0]
	v_cvt_pk_bf16_f32 v18, v18, v19
	v_cvt_pk_bf16_f32 v19, v20, v21
	v_cvt_pk_bf16_f32 v0, v0, v1
	v_cvt_pk_bf16_f32 v1, v2, v3
	v_pk_mul_f32 v[2:3], v[12:13], v[72:73] op_sel_hi:[1,0]
	v_pk_mul_f32 v[4:5], v[14:15], v[72:73] op_sel_hi:[1,0]
	v_pk_mul_f32 v[48:49], v[48:49], v[72:73] op_sel_hi:[1,0]
	v_pk_mul_f32 v[50:51], v[50:51], v[72:73] op_sel_hi:[1,0]
	v_pk_mul_f32 v[32:33], v[32:33], v[72:73] op_sel_hi:[1,0]
	v_pk_mul_f32 v[34:35], v[34:35], v[72:73] op_sel_hi:[1,0]
	ds_write2_b64 v74, v[16:17], v[18:19] offset0:20 offset1:22
	v_cvt_pk_bf16_f32 v2, v2, v3
	v_cvt_pk_bf16_f32 v3, v4, v5
	v_cvt_pk_bf16_f32 v48, v48, v49
	v_cvt_pk_bf16_f32 v49, v50, v51
	v_pk_mul_f32 v[50:51], v[52:53], v[72:73] op_sel_hi:[1,0]
	v_pk_mul_f32 v[52:53], v[54:55], v[72:73] op_sel_hi:[1,0]
	v_cvt_pk_bf16_f32 v32, v32, v33
	v_cvt_pk_bf16_f32 v33, v34, v35
	v_pk_mul_f32 v[34:35], v[36:37], v[72:73] op_sel_hi:[1,0]
	v_pk_mul_f32 v[36:37], v[38:39], v[72:73] op_sel_hi:[1,0]
	ds_write2_b64 v74, v[0:1], v[2:3] offset0:28 offset1:30
	v_cvt_pk_bf16_f32 v50, v50, v51
	v_cvt_pk_bf16_f32 v51, v52, v53
	v_cvt_pk_bf16_f32 v34, v34, v35
	v_cvt_pk_bf16_f32 v35, v36, v37
	ds_write2_b64 v74, v[48:49], v[50:51] offset1:2
	v_pk_mul_f32 v[48:49], v[56:57], v[72:73] op_sel_hi:[1,0]
	v_pk_mul_f32 v[50:51], v[58:59], v[72:73] op_sel_hi:[1,0]
	ds_write2_b64 v74, v[32:33], v[34:35] offset0:8 offset1:10
	v_pk_mul_f32 v[32:33], v[40:41], v[72:73] op_sel_hi:[1,0]
	v_pk_mul_f32 v[34:35], v[42:43], v[72:73] op_sel_hi:[1,0]
	v_cvt_pk_bf16_f32 v48, v48, v49
	v_cvt_pk_bf16_f32 v49, v50, v51
	v_pk_mul_f32 v[50:51], v[60:61], v[72:73] op_sel_hi:[1,0]
	v_pk_mul_f32 v[52:53], v[62:63], v[72:73] op_sel_hi:[1,0]
	v_cvt_pk_bf16_f32 v32, v32, v33
	v_cvt_pk_bf16_f32 v33, v34, v35
	v_pk_mul_f32 v[34:35], v[44:45], v[72:73] op_sel_hi:[1,0]
	v_pk_mul_f32 v[36:37], v[46:47], v[72:73] op_sel_hi:[1,0]
	v_cvt_pk_bf16_f32 v50, v50, v51
	v_cvt_pk_bf16_f32 v51, v52, v53
	v_cvt_pk_bf16_f32 v34, v34, v35
	s_waitcnt vmcnt(7)
	v_lshlrev_b32_e32 v16, 16, v64
	v_and_b32_e32 v14, 0xffff0000, v64
	v_mul_f32_e32 v0, 0xbfb8aa3b, v16
	v_mul_f32_e32 v1, 0xbfb8aa3b, v14
	v_exp_f32_e32 v0, v0
	v_exp_f32_e32 v1, v1
	v_cvt_pk_bf16_f32 v35, v36, v37
	ds_write2_b64 v74, v[48:49], v[50:51] offset0:4 offset1:6
	ds_write2_b64 v74, v[32:33], v[34:35] offset0:12 offset1:14
	v_mad_u64_u32 v[12:13], s[6:7], v144, s69, v[148:149]
	v_pk_add_f32 v[8:9], v[0:1], 1.0 op_sel_hi:[1,0]
	ds_read_b128 v[4:7], v12
	ds_read_b128 v[0:3], v12 offset:1088
	s_waitcnt lgkmcnt(1)
	v_lshlrev_b32_e32 v10, 16, v4
	v_and_b32_e32 v11, 0xffff0000, v4
	v_and_b32_e32 v19, 0xffff0000, v65
	v_rcp_f32_e32 v4, v9
	s_nop 0
	v_mul_f32_e32 v9, v14, v4
	v_mul_f32_e32 v15, 0xbfb8aa3b, v19
	v_lshlrev_b32_e32 v13, 16, v65
	v_mul_f32_e32 v14, 0xbfb8aa3b, v13
	v_exp_f32_e32 v14, v14
	v_exp_f32_e32 v15, v15
	v_rcp_f32_e32 v4, v8
	s_nop 0
	v_mul_f32_e32 v8, v16, v4
	v_pk_mul_f32 v[8:9], v[8:9], v[10:11]
	v_pk_add_f32 v[10:11], v[14:15], 1.0 op_sel_hi:[1,0]
	v_cvt_pk_bf16_f32 v4, v8, v9
	v_lshlrev_b32_e32 v8, 16, v5
	v_and_b32_e32 v9, 0xffff0000, v5
	v_lshlrev_b32_e32 v18, 16, v66
	v_rcp_f32_e32 v5, v11
	s_nop 0
	v_mul_f32_e32 v11, v19, v5
	v_and_b32_e32 v19, 0xffff0000, v66
	v_mul_f32_e32 v14, 0xbfb8aa3b, v18
	v_mul_f32_e32 v15, 0xbfb8aa3b, v19
	v_exp_f32_e32 v14, v14
	v_exp_f32_e32 v15, v15
	v_rcp_f32_e32 v5, v10
	s_nop 0
	v_mul_f32_e32 v10, v13, v5
	v_pk_mul_f32 v[8:9], v[10:11], v[8:9]
	v_pk_add_f32 v[10:11], v[14:15], 1.0 op_sel_hi:[1,0]
	v_cvt_pk_bf16_f32 v5, v8, v9
	v_lshlrev_b32_e32 v8, 16, v6
	v_and_b32_e32 v9, 0xffff0000, v6
	v_rcp_f32_e32 v6, v11
	s_nop 0
	v_mul_f32_e32 v11, v19, v6
	v_and_b32_e32 v19, 0xffff0000, v67
	v_lshlrev_b32_e32 v13, 16, v67
	v_mul_f32_e32 v14, 0xbfb8aa3b, v13
	v_mul_f32_e32 v15, 0xbfb8aa3b, v19
	v_exp_f32_e32 v14, v14
	v_exp_f32_e32 v15, v15
	v_rcp_f32_e32 v6, v10
	s_nop 0
	v_mul_f32_e32 v10, v18, v6
	v_pk_mul_f32 v[8:9], v[10:11], v[8:9]
	v_pk_add_f32 v[10:11], v[14:15], 1.0 op_sel_hi:[1,0]
	v_cvt_pk_bf16_f32 v6, v8, v9
	v_lshlrev_b32_e32 v8, 16, v7
	v_and_b32_e32 v9, 0xffff0000, v7
	v_rcp_f32_e32 v7, v11
	s_nop 0
	v_mul_f32_e32 v11, v19, v7
	v_rcp_f32_e32 v7, v10
	s_nop 0
	v_mul_f32_e32 v10, v13, v7
	v_pk_mul_f32 v[8:9], v[10:11], v[8:9]
	s_waitcnt lgkmcnt(0)
	v_lshlrev_b32_e32 v14, 16, v0
	v_cvt_pk_bf16_f32 v7, v8, v9
	v_lshlrev_b64 v[8:9], 12, v[144:145]
	v_lshl_add_u64 v[8:9], v[68:69], 0, v[8:9]
	global_store_dwordx4 v[8:9], v[4:7], off sc1
	v_or_b32_e32 v8, 4, v144
	v_and_b32_e32 v15, 0xffff0000, v0
	v_mad_u64_u32 v[4:5], s[6:7], v8, s72, v[70:71]
	s_waitcnt vmcnt(7)
	v_mov_b32_e32 v4, v100
	v_mov_b32_e32 v5, v101
	v_mov_b32_e32 v6, v102
	v_mov_b32_e32 v7, v103
	v_lshlrev_b32_e32 v13, 16, v4
	v_and_b32_e32 v4, 0xffff0000, v4
	v_mul_f32_e32 v9, 0xbfb8aa3b, v13
	v_exp_f32_e32 v10, v9
	v_mul_f32_e32 v9, 0xbfb8aa3b, v4
	v_exp_f32_e32 v11, v9
	v_mov_b32_e32 v9, v145
	v_pk_add_f32 v[10:11], v[10:11], 1.0 op_sel_hi:[1,0]
	s_nop 0
	s_nop 0
	v_rcp_f32_e32 v0, v11
	s_nop 0
	v_mul_f32_e32 v11, v4, v0
	v_and_b32_e32 v18, 0xffff0000, v5
	v_lshlrev_b32_e32 v16, 16, v5
	v_mul_f32_e32 v4, 0xbfb8aa3b, v16
	v_mul_f32_e32 v5, 0xbfb8aa3b, v18
	v_exp_f32_e32 v4, v4
	v_exp_f32_e32 v5, v5
	v_rcp_f32_e32 v0, v10
	s_nop 0
	v_mul_f32_e32 v10, v13, v0
	v_pk_mul_f32 v[10:11], v[10:11], v[14:15]
	v_pk_add_f32 v[4:5], v[4:5], 1.0 op_sel_hi:[1,0]
	v_cvt_pk_bf16_f32 v0, v10, v11
	v_lshlrev_b32_e32 v10, 16, v1
	v_and_b32_e32 v11, 0xffff0000, v1
	v_rcp_f32_e32 v1, v5
	s_nop 0
	v_mul_f32_e32 v5, v18, v1
	v_lshlrev_b32_e32 v13, 16, v6
	v_and_b32_e32 v6, 0xffff0000, v6
	v_mul_f32_e32 v14, 0xbfb8aa3b, v13
	v_mul_f32_e32 v15, 0xbfb8aa3b, v6
	v_exp_f32_e32 v14, v14
	v_exp_f32_e32 v15, v15
	v_rcp_f32_e32 v1, v4
	s_nop 0
	v_mul_f32_e32 v4, v16, v1
	v_pk_mul_f32 v[4:5], v[4:5], v[10:11]
	v_pk_add_f32 v[10:11], v[14:15], 1.0 op_sel_hi:[1,0]
	v_cvt_pk_bf16_f32 v1, v4, v5
	v_lshlrev_b32_e32 v4, 16, v2
	v_and_b32_e32 v5, 0xffff0000, v2
	v_rcp_f32_e32 v2, v11
	s_nop 0
	v_mul_f32_e32 v11, v6, v2
	v_and_b32_e32 v16, 0xffff0000, v7
	v_lshlrev_b32_e32 v14, 16, v7
	v_mul_f32_e32 v6, 0xbfb8aa3b, v14
	v_mul_f32_e32 v7, 0xbfb8aa3b, v16
	v_exp_f32_e32 v6, v6
	v_exp_f32_e32 v7, v7
	v_rcp_f32_e32 v2, v10
	s_nop 0
	v_mul_f32_e32 v10, v13, v2
	v_pk_mul_f32 v[4:5], v[10:11], v[4:5]
	v_pk_add_f32 v[6:7], v[6:7], 1.0 op_sel_hi:[1,0]
	v_cvt_pk_bf16_f32 v2, v4, v5
	v_lshlrev_b32_e32 v4, 16, v3
	v_and_b32_e32 v5, 0xffff0000, v3
	v_rcp_f32_e32 v3, v7
	s_nop 0
	v_mul_f32_e32 v7, v16, v3
	v_rcp_f32_e32 v3, v6
	s_nop 0
	v_mul_f32_e32 v6, v14, v3
	v_pk_mul_f32 v[4:5], v[6:7], v[4:5]
	v_or_b32_e32 v14, 8, v144
	v_cvt_pk_bf16_f32 v3, v4, v5
	v_lshlrev_b64 v[4:5], 12, v[8:9]
	v_lshl_add_u64 v[4:5], v[68:69], 0, v[4:5]
	global_store_dwordx4 v[4:5], v[0:3], off sc1
	ds_read_b128 v[4:7], v12 offset:2176
	v_mov_b32_e32 v15, v145
	v_mad_u64_u32 v[0:1], s[6:7], v14, s72, v[70:71]
	s_waitcnt vmcnt(7)
	v_mov_b32_e32 v8, v104
	v_mov_b32_e32 v9, v105
	v_mov_b32_e32 v10, v106
	v_mov_b32_e32 v11, v107
	v_lshlrev_b32_e32 v13, 16, v8
	v_and_b32_e32 v8, 0xffff0000, v8
	v_mul_f32_e32 v0, 0xbfb8aa3b, v13
	v_mul_f32_e32 v1, 0xbfb8aa3b, v8
	v_exp_f32_e32 v0, v0
	v_exp_f32_e32 v1, v1
	s_nop 0
	v_pk_add_f32 v[16:17], v[0:1], 1.0 op_sel_hi:[1,0]
	s_nop 0
	ds_read_b128 v[0:3], v12 offset:3264
	s_waitcnt lgkmcnt(1)
	v_lshlrev_b32_e32 v18, 16, v4
	v_and_b32_e32 v19, 0xffff0000, v4
	v_rcp_f32_e32 v4, v17
	s_nop 0
	v_mul_f32_e32 v17, v8, v4
	v_and_b32_e32 v22, 0xffff0000, v9
	v_lshlrev_b32_e32 v20, 16, v9
	v_mul_f32_e32 v8, 0xbfb8aa3b, v20
	v_mul_f32_e32 v9, 0xbfb8aa3b, v22
	v_exp_f32_e32 v8, v8
	v_exp_f32_e32 v9, v9
	v_rcp_f32_e32 v4, v16
	s_nop 0
	v_mul_f32_e32 v16, v13, v4
	v_pk_mul_f32 v[16:17], v[16:17], v[18:19]
	v_pk_add_f32 v[8:9], v[8:9], 1.0 op_sel_hi:[1,0]
	v_cvt_pk_bf16_f32 v4, v16, v17
	v_lshlrev_b32_e32 v16, 16, v5
	v_and_b32_e32 v17, 0xffff0000, v5
	v_rcp_f32_e32 v5, v9
	s_nop 0
	v_mul_f32_e32 v9, v22, v5
	v_lshlrev_b32_e32 v13, 16, v10
	v_and_b32_e32 v10, 0xffff0000, v10
	v_mul_f32_e32 v18, 0xbfb8aa3b, v13
	v_mul_f32_e32 v19, 0xbfb8aa3b, v10
	v_exp_f32_e32 v18, v18
	v_exp_f32_e32 v19, v19
	v_rcp_f32_e32 v5, v8
	s_nop 0
	v_mul_f32_e32 v8, v20, v5
	v_pk_mul_f32 v[8:9], v[8:9], v[16:17]
	v_pk_add_f32 v[16:17], v[18:19], 1.0 op_sel_hi:[1,0]
	v_cvt_pk_bf16_f32 v5, v8, v9
	v_lshlrev_b32_e32 v8, 16, v6
	v_and_b32_e32 v9, 0xffff0000, v6
	v_rcp_f32_e32 v6, v17
	s_nop 0
	v_mul_f32_e32 v17, v10, v6
	v_and_b32_e32 v20, 0xffff0000, v11
	v_lshlrev_b32_e32 v18, 16, v11
	v_mul_f32_e32 v10, 0xbfb8aa3b, v18
	v_mul_f32_e32 v11, 0xbfb8aa3b, v20
	v_exp_f32_e32 v10, v10
	v_exp_f32_e32 v11, v11
	v_rcp_f32_e32 v6, v16
	s_nop 0
	v_mul_f32_e32 v16, v13, v6
	v_pk_mul_f32 v[8:9], v[16:17], v[8:9]
	v_pk_add_f32 v[10:11], v[10:11], 1.0 op_sel_hi:[1,0]
	v_cvt_pk_bf16_f32 v6, v8, v9
	v_lshlrev_b32_e32 v8, 16, v7
	v_and_b32_e32 v9, 0xffff0000, v7
	v_rcp_f32_e32 v7, v11
	s_nop 0
	v_mul_f32_e32 v11, v20, v7
	v_rcp_f32_e32 v7, v10
	s_nop 0
	v_mul_f32_e32 v10, v18, v7
	v_pk_mul_f32 v[8:9], v[10:11], v[8:9]
	s_nop 0
	v_cvt_pk_bf16_f32 v7, v8, v9
	v_lshlrev_b64 v[8:9], 12, v[14:15]
	v_lshl_add_u64 v[8:9], v[68:69], 0, v[8:9]
	global_store_dwordx4 v[8:9], v[4:7], off sc1
	v_or_b32_e32 v8, 12, v144
	s_waitcnt lgkmcnt(0)
	v_lshlrev_b32_e32 v14, 16, v0
	v_mad_u64_u32 v[4:5], s[6:7], v8, s72, v[70:71]
	v_and_b32_e32 v15, 0xffff0000, v0
	s_waitcnt vmcnt(7)
	v_mov_b32_e32 v4, v108
	v_mov_b32_e32 v5, v109
	v_mov_b32_e32 v6, v110
	v_mov_b32_e32 v7, v111
	v_lshlrev_b32_e32 v13, 16, v4
	v_and_b32_e32 v4, 0xffff0000, v4
	v_mul_f32_e32 v9, 0xbfb8aa3b, v13
	v_exp_f32_e32 v10, v9
	v_mul_f32_e32 v9, 0xbfb8aa3b, v4
	v_exp_f32_e32 v11, v9
	v_mov_b32_e32 v9, v145
	v_pk_add_f32 v[10:11], v[10:11], 1.0 op_sel_hi:[1,0]
	s_nop 0
	s_nop 0
	v_rcp_f32_e32 v0, v11
	s_nop 0
	v_mul_f32_e32 v11, v4, v0
	v_and_b32_e32 v18, 0xffff0000, v5
	v_lshlrev_b32_e32 v16, 16, v5
	v_mul_f32_e32 v4, 0xbfb8aa3b, v16
	v_mul_f32_e32 v5, 0xbfb8aa3b, v18
	v_exp_f32_e32 v4, v4
	v_exp_f32_e32 v5, v5
	v_rcp_f32_e32 v0, v10
	s_nop 0
	v_mul_f32_e32 v10, v13, v0
	v_pk_mul_f32 v[10:11], v[10:11], v[14:15]
	v_pk_add_f32 v[4:5], v[4:5], 1.0 op_sel_hi:[1,0]
	v_cvt_pk_bf16_f32 v0, v10, v11
	v_lshlrev_b32_e32 v10, 16, v1
	v_and_b32_e32 v11, 0xffff0000, v1
	v_rcp_f32_e32 v1, v5
	s_nop 0
	v_mul_f32_e32 v5, v18, v1
	v_lshlrev_b32_e32 v13, 16, v6
	v_and_b32_e32 v6, 0xffff0000, v6
	v_mul_f32_e32 v14, 0xbfb8aa3b, v13
	v_mul_f32_e32 v15, 0xbfb8aa3b, v6
	v_exp_f32_e32 v14, v14
	v_exp_f32_e32 v15, v15
	v_rcp_f32_e32 v1, v4
	s_nop 0
	v_mul_f32_e32 v4, v16, v1
	v_pk_mul_f32 v[4:5], v[4:5], v[10:11]
	v_pk_add_f32 v[10:11], v[14:15], 1.0 op_sel_hi:[1,0]
	v_cvt_pk_bf16_f32 v1, v4, v5
	v_lshlrev_b32_e32 v4, 16, v2
	v_and_b32_e32 v5, 0xffff0000, v2
	v_rcp_f32_e32 v2, v11
	s_nop 0
	v_mul_f32_e32 v11, v6, v2
	v_and_b32_e32 v16, 0xffff0000, v7
	v_lshlrev_b32_e32 v14, 16, v7
	v_mul_f32_e32 v6, 0xbfb8aa3b, v14
	v_mul_f32_e32 v7, 0xbfb8aa3b, v16
	v_exp_f32_e32 v6, v6
	v_exp_f32_e32 v7, v7
	v_rcp_f32_e32 v2, v10
	s_nop 0
	v_mul_f32_e32 v10, v13, v2
	v_pk_mul_f32 v[4:5], v[10:11], v[4:5]
	v_pk_add_f32 v[6:7], v[6:7], 1.0 op_sel_hi:[1,0]
	v_cvt_pk_bf16_f32 v2, v4, v5
	v_lshlrev_b32_e32 v4, 16, v3
	v_and_b32_e32 v5, 0xffff0000, v3
	v_rcp_f32_e32 v3, v7
	s_nop 0
	v_mul_f32_e32 v7, v16, v3
	v_rcp_f32_e32 v3, v6
	s_nop 0
	v_mul_f32_e32 v6, v14, v3
	v_pk_mul_f32 v[4:5], v[6:7], v[4:5]
	v_or_b32_e32 v14, 16, v144
	v_cvt_pk_bf16_f32 v3, v4, v5
	v_lshlrev_b64 v[4:5], 12, v[8:9]
	v_lshl_add_u64 v[4:5], v[68:69], 0, v[4:5]
	global_store_dwordx4 v[4:5], v[0:3], off sc1
	ds_read_b128 v[4:7], v12 offset:4352
	v_mov_b32_e32 v15, v145
	v_mad_u64_u32 v[0:1], s[6:7], v14, s72, v[70:71]
	s_waitcnt vmcnt(7)
	v_mov_b32_e32 v8, v112
	v_mov_b32_e32 v9, v113
	v_mov_b32_e32 v10, v114
	v_mov_b32_e32 v11, v115
	v_lshlrev_b32_e32 v13, 16, v8
	v_and_b32_e32 v8, 0xffff0000, v8
	v_mul_f32_e32 v0, 0xbfb8aa3b, v13
	v_mul_f32_e32 v1, 0xbfb8aa3b, v8
	v_exp_f32_e32 v0, v0
	v_exp_f32_e32 v1, v1
	s_nop 0
	v_pk_add_f32 v[16:17], v[0:1], 1.0 op_sel_hi:[1,0]
	s_nop 0
	ds_read_b128 v[0:3], v12 offset:5440
	s_waitcnt lgkmcnt(1)
	v_lshlrev_b32_e32 v18, 16, v4
	v_and_b32_e32 v19, 0xffff0000, v4
	v_div_scale_f32 v20, s[6:7], v16, v16, v13
	v_rcp_f32_e32 v23, v20
	v_rcp_f32_e32 v4, v17
	s_nop 0
	v_mul_f32_e32 v17, v8, v4
	v_and_b32_e32 v22, 0xffff0000, v9
	v_fma_f32 v4, -v20, v23, 1.0
	v_fmac_f32_e32 v23, v4, v23
	v_lshlrev_b32_e32 v20, 16, v9
	v_mul_f32_e32 v8, 0xbfb8aa3b, v20
	v_mul_f32_e32 v9, 0xbfb8aa3b, v22
	v_exp_f32_e32 v8, v8
	v_exp_f32_e32 v9, v9
	v_rcp_f32_e32 v4, v16
	s_nop 0
	v_mul_f32_e32 v16, v13, v4
	v_pk_mul_f32 v[16:17], v[16:17], v[18:19]
	v_pk_add_f32 v[8:9], v[8:9], 1.0 op_sel_hi:[1,0]
	v_cvt_pk_bf16_f32 v4, v16, v17
	v_lshlrev_b32_e32 v16, 16, v5
	v_and_b32_e32 v17, 0xffff0000, v5
	v_rcp_f32_e32 v5, v9
	s_nop 0
	v_mul_f32_e32 v9, v22, v5
	v_lshlrev_b32_e32 v13, 16, v10
	v_and_b32_e32 v10, 0xffff0000, v10
	v_mul_f32_e32 v18, 0xbfb8aa3b, v13
	v_mul_f32_e32 v19, 0xbfb8aa3b, v10
	v_exp_f32_e32 v18, v18
	v_exp_f32_e32 v19, v19
	v_rcp_f32_e32 v5, v8
	s_nop 0
	v_mul_f32_e32 v8, v20, v5
	v_pk_mul_f32 v[8:9], v[8:9], v[16:17]
	v_pk_add_f32 v[16:17], v[18:19], 1.0 op_sel_hi:[1,0]
	v_cvt_pk_bf16_f32 v5, v8, v9
	v_lshlrev_b32_e32 v8, 16, v6
	v_and_b32_e32 v9, 0xffff0000, v6
	v_rcp_f32_e32 v6, v17
	s_nop 0
	v_mul_f32_e32 v17, v10, v6
	v_and_b32_e32 v20, 0xffff0000, v11
	v_lshlrev_b32_e32 v18, 16, v11
	v_mul_f32_e32 v10, 0xbfb8aa3b, v18
	v_mul_f32_e32 v11, 0xbfb8aa3b, v20
	v_exp_f32_e32 v10, v10
	v_exp_f32_e32 v11, v11
	v_rcp_f32_e32 v6, v16
	s_nop 0
	v_mul_f32_e32 v16, v13, v6
	v_pk_mul_f32 v[8:9], v[16:17], v[8:9]
	v_pk_add_f32 v[10:11], v[10:11], 1.0 op_sel_hi:[1,0]
	v_cvt_pk_bf16_f32 v6, v8, v9
	v_lshlrev_b32_e32 v8, 16, v7
	v_and_b32_e32 v9, 0xffff0000, v7
	v_rcp_f32_e32 v7, v11
	s_nop 0
	v_mul_f32_e32 v11, v20, v7
	v_rcp_f32_e32 v7, v10
	s_nop 0
	v_mul_f32_e32 v10, v18, v7
	v_pk_mul_f32 v[8:9], v[10:11], v[8:9]
	s_nop 0
	v_cvt_pk_bf16_f32 v7, v8, v9
	v_lshlrev_b64 v[8:9], 12, v[14:15]
	v_lshl_add_u64 v[8:9], v[68:69], 0, v[8:9]
	global_store_dwordx4 v[8:9], v[4:7], off sc1
	v_or_b32_e32 v8, 20, v144
	s_waitcnt lgkmcnt(0)
	v_lshlrev_b32_e32 v14, 16, v0
	v_mad_u64_u32 v[4:5], s[6:7], v8, s72, v[70:71]
	v_and_b32_e32 v15, 0xffff0000, v0
	s_waitcnt vmcnt(7)
	v_mov_b32_e32 v4, v116
	v_mov_b32_e32 v5, v117
	v_mov_b32_e32 v6, v118
	v_mov_b32_e32 v7, v119
	v_lshlrev_b32_e32 v13, 16, v4
	v_and_b32_e32 v4, 0xffff0000, v4
	v_mul_f32_e32 v9, 0xbfb8aa3b, v13
	v_exp_f32_e32 v10, v9
	v_mul_f32_e32 v9, 0xbfb8aa3b, v4
	v_exp_f32_e32 v11, v9
	v_mov_b32_e32 v9, v145
	v_pk_add_f32 v[10:11], v[10:11], 1.0 op_sel_hi:[1,0]
	s_nop 0
	s_nop 0
	v_rcp_f32_e32 v0, v11
	s_nop 0
	v_mul_f32_e32 v11, v4, v0
	v_and_b32_e32 v18, 0xffff0000, v5
	v_lshlrev_b32_e32 v16, 16, v5
	v_mul_f32_e32 v4, 0xbfb8aa3b, v16
	v_mul_f32_e32 v5, 0xbfb8aa3b, v18
	v_exp_f32_e32 v4, v4
	v_exp_f32_e32 v5, v5
	v_rcp_f32_e32 v0, v10
	s_nop 0
	v_mul_f32_e32 v10, v13, v0
	v_pk_mul_f32 v[10:11], v[10:11], v[14:15]
	v_pk_add_f32 v[4:5], v[4:5], 1.0 op_sel_hi:[1,0]
	v_cvt_pk_bf16_f32 v0, v10, v11
	v_lshlrev_b32_e32 v10, 16, v1
	v_and_b32_e32 v11, 0xffff0000, v1
	v_rcp_f32_e32 v1, v5
	s_nop 0
	v_mul_f32_e32 v5, v18, v1
	v_lshlrev_b32_e32 v13, 16, v6
	v_and_b32_e32 v6, 0xffff0000, v6
	v_mul_f32_e32 v14, 0xbfb8aa3b, v13
	v_mul_f32_e32 v15, 0xbfb8aa3b, v6
	v_exp_f32_e32 v14, v14
	v_exp_f32_e32 v15, v15
	v_rcp_f32_e32 v1, v4
	s_nop 0
	v_mul_f32_e32 v4, v16, v1
	v_pk_mul_f32 v[4:5], v[4:5], v[10:11]
	v_pk_add_f32 v[10:11], v[14:15], 1.0 op_sel_hi:[1,0]
	v_cvt_pk_bf16_f32 v1, v4, v5
	v_lshlrev_b32_e32 v4, 16, v2
	v_and_b32_e32 v5, 0xffff0000, v2
	v_rcp_f32_e32 v2, v11
	s_nop 0
	v_mul_f32_e32 v11, v6, v2
	v_and_b32_e32 v16, 0xffff0000, v7
	v_lshlrev_b32_e32 v14, 16, v7
	v_mul_f32_e32 v6, 0xbfb8aa3b, v14
	v_mul_f32_e32 v7, 0xbfb8aa3b, v16
	v_exp_f32_e32 v6, v6
	v_exp_f32_e32 v7, v7
	v_rcp_f32_e32 v2, v10
	s_nop 0
	v_mul_f32_e32 v10, v13, v2
	v_pk_mul_f32 v[4:5], v[10:11], v[4:5]
	v_pk_add_f32 v[6:7], v[6:7], 1.0 op_sel_hi:[1,0]
	v_cvt_pk_bf16_f32 v2, v4, v5
	v_lshlrev_b32_e32 v4, 16, v3
	v_and_b32_e32 v5, 0xffff0000, v3
	v_rcp_f32_e32 v3, v7
	s_nop 0
	v_mul_f32_e32 v7, v16, v3
	v_rcp_f32_e32 v3, v6
	s_nop 0
	v_mul_f32_e32 v6, v14, v3
	v_pk_mul_f32 v[4:5], v[6:7], v[4:5]
	v_or_b32_e32 v14, 24, v144
	v_cvt_pk_bf16_f32 v3, v4, v5
	v_lshlrev_b64 v[4:5], 12, v[8:9]
	v_lshl_add_u64 v[4:5], v[68:69], 0, v[4:5]
	global_store_dwordx4 v[4:5], v[0:3], off sc1
	ds_read_b128 v[4:7], v12 offset:6528
	v_mov_b32_e32 v15, v145
	v_mad_u64_u32 v[0:1], s[6:7], v14, s72, v[70:71]
	v_or_b32_e32 v144, 28, v144
	s_waitcnt vmcnt(7)
	v_mov_b32_e32 v8, v120
	v_mov_b32_e32 v9, v121
	v_mov_b32_e32 v10, v122
	v_mov_b32_e32 v11, v123
	v_lshlrev_b32_e32 v18, 16, v8
	v_and_b32_e32 v8, 0xffff0000, v8
	v_mul_f32_e32 v0, 0xbfb8aa3b, v18
	v_mul_f32_e32 v1, 0xbfb8aa3b, v8
	v_exp_f32_e32 v0, v0
	v_exp_f32_e32 v1, v1
	s_nop 0
	v_pk_add_f32 v[16:17], v[0:1], 1.0 op_sel_hi:[1,0]
	s_nop 0
	ds_read_b128 v[0:3], v12 offset:7616
	s_waitcnt lgkmcnt(1)
	v_lshlrev_b32_e32 v12, 16, v4
	v_and_b32_e32 v13, 0xffff0000, v4
	v_div_scale_f32 v19, s[6:7], v16, v16, v18
	v_rcp_f32_e32 v22, v19
	v_rcp_f32_e32 v4, v17
	s_nop 0
	v_mul_f32_e32 v17, v8, v4
	v_and_b32_e32 v21, 0xffff0000, v9
	v_fma_f32 v4, -v19, v22, 1.0
	v_fmac_f32_e32 v22, v4, v22
	v_lshlrev_b32_e32 v19, 16, v9
	v_mul_f32_e32 v8, 0xbfb8aa3b, v19
	v_mul_f32_e32 v9, 0xbfb8aa3b, v21
	v_exp_f32_e32 v8, v8
	v_exp_f32_e32 v9, v9
	v_rcp_f32_e32 v4, v16
	s_nop 0
	v_mul_f32_e32 v16, v18, v4
	v_pk_mul_f32 v[12:13], v[16:17], v[12:13]
	v_pk_add_f32 v[8:9], v[8:9], 1.0 op_sel_hi:[1,0]
	v_cvt_pk_bf16_f32 v4, v12, v13
	v_lshlrev_b32_e32 v12, 16, v5
	v_and_b32_e32 v13, 0xffff0000, v5
	v_div_scale_f32 v16, s[6:7], v8, v8, v19
	v_rcp_f32_e32 v20, v16
	v_rcp_f32_e32 v5, v9
	s_nop 0
	v_mul_f32_e32 v9, v21, v5
	v_lshlrev_b32_e32 v21, 16, v10
	v_fma_f32 v5, -v16, v20, 1.0
	v_fmac_f32_e32 v20, v5, v20
	v_and_b32_e32 v10, 0xffff0000, v10
	v_mul_f32_e32 v16, 0xbfb8aa3b, v21
	v_mul_f32_e32 v17, 0xbfb8aa3b, v10
	v_exp_f32_e32 v16, v16
	v_exp_f32_e32 v17, v17
	v_rcp_f32_e32 v5, v8
	s_nop 0
	v_mul_f32_e32 v8, v19, v5
	v_pk_mul_f32 v[8:9], v[8:9], v[12:13]
	v_pk_add_f32 v[12:13], v[16:17], 1.0 op_sel_hi:[1,0]
	v_cvt_pk_bf16_f32 v5, v8, v9
	v_lshlrev_b32_e32 v8, 16, v6
	v_and_b32_e32 v9, 0xffff0000, v6
	v_rcp_f32_e32 v6, v13
	s_nop 0
	v_mul_f32_e32 v13, v10, v6
	v_and_b32_e32 v18, 0xffff0000, v11
	v_lshlrev_b32_e32 v16, 16, v11
	v_mul_f32_e32 v10, 0xbfb8aa3b, v16
	v_mul_f32_e32 v11, 0xbfb8aa3b, v18
	v_exp_f32_e32 v10, v10
	v_exp_f32_e32 v11, v11
	v_rcp_f32_e32 v6, v12
	s_nop 0
	v_mul_f32_e32 v12, v21, v6
	v_pk_mul_f32 v[8:9], v[12:13], v[8:9]
	v_pk_add_f32 v[10:11], v[10:11], 1.0 op_sel_hi:[1,0]
	v_cvt_pk_bf16_f32 v6, v8, v9
	v_lshlrev_b32_e32 v8, 16, v7
	v_and_b32_e32 v9, 0xffff0000, v7
	v_div_scale_f32 v12, s[6:7], v10, v10, v16
	v_rcp_f32_e32 v19, v12
	v_rcp_f32_e32 v7, v11
	s_nop 0
	v_mul_f32_e32 v11, v18, v7
	v_fma_f32 v7, -v12, v19, 1.0
	v_fmac_f32_e32 v19, v7, v19
	v_div_scale_f32 v7, vcc, v16, v10, v16
	v_mul_f32_e32 v13, v7, v19
	v_fma_f32 v17, -v12, v13, v7
	v_rcp_f32_e32 v7, v10
	s_nop 0
	v_mul_f32_e32 v10, v16, v7
	v_pk_mul_f32 v[8:9], v[10:11], v[8:9]
	s_waitcnt lgkmcnt(0)
	v_lshlrev_b32_e32 v10, 16, v0
	v_cvt_pk_bf16_f32 v7, v8, v9
	v_lshlrev_b64 v[8:9], 12, v[14:15]
	v_lshl_add_u64 v[8:9], v[68:69], 0, v[8:9]
	global_store_dwordx4 v[8:9], v[4:7], off sc1
	v_and_b32_e32 v11, 0xffff0000, v0
	s_nop 0
	v_mad_u64_u32 v[4:5], s[6:7], v144, s72, v[70:71]
	s_waitcnt vmcnt(7)
	v_mov_b32_e32 v4, v124
	v_mov_b32_e32 v5, v125
	v_mov_b32_e32 v6, v126
	v_mov_b32_e32 v7, v127
	v_lshlrev_b32_e32 v12, 16, v4
	v_and_b32_e32 v4, 0xffff0000, v4
	v_mul_f32_e32 v8, 0xbfb8aa3b, v12
	v_mul_f32_e32 v9, 0xbfb8aa3b, v4
	v_exp_f32_e32 v8, v8
	v_exp_f32_e32 v9, v9
	s_nop 0
	v_pk_add_f32 v[8:9], v[8:9], 1.0 op_sel_hi:[1,0]
	s_nop 0
	s_nop 0
	v_div_scale_f32 v13, s[6:7], v8, v8, v12
	v_rcp_f32_e32 v16, v13
	v_rcp_f32_e32 v0, v9
	s_nop 0
	v_mul_f32_e32 v9, v4, v0
	v_and_b32_e32 v15, 0xffff0000, v5
	v_fma_f32 v0, -v13, v16, 1.0
	v_fmac_f32_e32 v16, v0, v16
	v_lshlrev_b32_e32 v13, 16, v5
	v_mul_f32_e32 v4, 0xbfb8aa3b, v13
	v_mul_f32_e32 v5, 0xbfb8aa3b, v15
	v_exp_f32_e32 v4, v4
	v_exp_f32_e32 v5, v5
	v_rcp_f32_e32 v0, v8
	s_nop 0
	v_mul_f32_e32 v8, v12, v0
	v_pk_mul_f32 v[8:9], v[8:9], v[10:11]
	v_pk_add_f32 v[4:5], v[4:5], 1.0 op_sel_hi:[1,0]
	v_cvt_pk_bf16_f32 v0, v8, v9
	v_lshlrev_b32_e32 v8, 16, v1
	v_and_b32_e32 v9, 0xffff0000, v1
	v_div_scale_f32 v10, s[6:7], v4, v4, v13
	v_rcp_f32_e32 v14, v10
	v_rcp_f32_e32 v1, v5
	s_nop 0
	v_mul_f32_e32 v5, v15, v1
	v_lshlrev_b32_e32 v15, 16, v6
	v_fma_f32 v1, -v10, v14, 1.0
	v_fmac_f32_e32 v14, v1, v14
	v_and_b32_e32 v6, 0xffff0000, v6
	v_mul_f32_e32 v10, 0xbfb8aa3b, v15
	v_mul_f32_e32 v11, 0xbfb8aa3b, v6
	v_exp_f32_e32 v10, v10
	v_exp_f32_e32 v11, v11
	v_rcp_f32_e32 v1, v4
	s_nop 0
	v_mul_f32_e32 v4, v13, v1
	v_pk_mul_f32 v[4:5], v[4:5], v[8:9]
	v_pk_add_f32 v[8:9], v[10:11], 1.0 op_sel_hi:[1,0]
	v_cvt_pk_bf16_f32 v1, v4, v5
	v_lshlrev_b32_e32 v4, 16, v2
	v_and_b32_e32 v5, 0xffff0000, v2
	v_rcp_f32_e32 v2, v9
	s_nop 0
	v_mul_f32_e32 v9, v6, v2
	v_and_b32_e32 v12, 0xffff0000, v7
	v_lshlrev_b32_e32 v10, 16, v7
	v_mul_f32_e32 v6, 0xbfb8aa3b, v10
	v_mul_f32_e32 v7, 0xbfb8aa3b, v12
	v_exp_f32_e32 v6, v6
	v_exp_f32_e32 v7, v7
	v_rcp_f32_e32 v2, v8
	s_nop 0
	v_mul_f32_e32 v8, v15, v2
	v_pk_mul_f32 v[4:5], v[8:9], v[4:5]
	v_pk_add_f32 v[6:7], v[6:7], 1.0 op_sel_hi:[1,0]
	v_cvt_pk_bf16_f32 v2, v4, v5
	v_lshlrev_b32_e32 v4, 16, v3
	v_and_b32_e32 v5, 0xffff0000, v3
	v_div_scale_f32 v8, s[6:7], v6, v6, v10
	v_rcp_f32_e32 v13, v8
	v_rcp_f32_e32 v3, v7
	s_nop 0
	v_mul_f32_e32 v7, v12, v3
	v_fma_f32 v3, -v8, v13, 1.0
	v_fmac_f32_e32 v13, v3, v13
	v_div_scale_f32 v3, vcc, v10, v6, v10
	v_mul_f32_e32 v9, v3, v13
	v_fma_f32 v11, -v8, v9, v3
	v_fmac_f32_e32 v9, v11, v13
	v_rcp_f32_e32 v3, v6
	s_nop 0
	v_mul_f32_e32 v6, v10, v3
	v_pk_mul_f32 v[4:5], v[6:7], v[4:5]
	s_nop 0
	v_cvt_pk_bf16_f32 v3, v4, v5
	v_lshlrev_b64 v[4:5], 12, v[144:145]
	v_lshl_add_u64 v[4:5], v[68:69], 0, v[4:5]
	global_store_dwordx4 v[4:5], v[0:3], off sc1
	s_barrier

.LBB0_1227:
	s_or_b64 exec, exec, s[6:7]
	s_waitcnt vmcnt(0) lgkmcnt(0)
	s_barrier
	ds_read_b32 v0, v236
	s_mov_b64 s[6:7], -1
	s_waitcnt lgkmcnt(0)
	s_barrier
	v_readfirstlane_b32 s84, v0
	s_cmpk_gt_u32 s84, 0x3ff
	s_cbranch_scc1 .LBB0_1222
	s_cmpk_gt_u32 s84, 0x2ff
	s_cbranch_scc0 .LBB0_1285
	s_add_i32 s6, s84, 0xfffffd00
	s_lshr_b32 s24, s6, 6
	s_lshl_b32 s7, s6, 8
	s_lshl_b64 s[38:39], s[24:25], 12
	s_and_b32 s7, s7, 0xf00
	s_or_b32 s38, s38, s7
	s_mul_hi_u32 s8, s38, 0x1e00
	s_mul_i32 s9, s39, 0x1e00
	s_mul_i32 s7, s38, 0x1e00
	s_add_i32 s8, s8, s9
	s_add_u32 s85, s61, s7
	s_addc_u32 s86, s62, s8
	s_lshl_b32 s6, s6, 3
	s_and_b32 s6, s6, 0x180
	s_lshl_b32 s87, s6, 1
	s_add_u32 s7, s85, s87
	s_addc_u32 s9, s86, 0
	s_add_u32 s8, s7, 0x1000
	s_addc_u32 s9, s9, 0
	s_lshl_b32 s24, s24, 8
	s_lshl_b64 s[10:11], s[24:25], 10
	s_add_u32 s7, s65, s10
	s_addc_u32 s10, s66, s11
	s_add_u32 s50, s7, s87
	v_readfirstlane_b32 s54, v213
	s_addc_u32 s51, s10, 0
	s_lshr_b32 s90, s54, 6
	s_lshl_b32 s82, s90, 5
	v_or_b32_e32 v180, s82, v212
	v_mov_b64_e32 v[0:1], s[8:9]
	v_mad_u64_u32 v[0:1], s[8:9], v180, s72, v[0:1]
	v_mov_b32_e32 v153, v145
	v_lshl_add_u64 v[0:1], v[0:1], 0, v[152:153]
	global_load_dwordx4 v[124:127], v[0:1], off nt
	global_load_dwordx4 v[120:123], v[0:1], off offset:32 nt
	global_load_dwordx4 v[116:119], v[0:1], off offset:64 nt
	global_load_dwordx4 v[112:115], v[0:1], off offset:96 nt
	global_load_dwordx4 v[108:111], v[0:1], off offset:128 nt
	global_load_dwordx4 v[104:107], v[0:1], off offset:160 nt
	global_load_dwordx4 v[100:103], v[0:1], off offset:192 nt
	global_load_dwordx4 v[96:99], v[0:1], off offset:224 nt
	s_lshl_b32 s88, s90, 10
	v_or_b32_e32 v0, s88, v147
	v_mul_hi_i32 v1, v0, s74
	v_lshrrev_b32_e32 v2, 31, v1
	v_ashrrev_i32_e32 v1, 7, v1
	v_add_u32_e32 v1, v1, v2
	v_mul_i32_i24_e32 v2, 0x110, v1
	v_sub_u32_e32 v2, v0, v2
	v_cmp_gt_i32_e32 vcc, s75, v2
	v_min_i32_e32 v1, 63, v1
	s_cmpk_lt_u32 s54, 0x440
	v_cndmask_b32_e32 v2, 0, v2, vcc
	s_cselect_b64 s[8:9], -1, 0
	s_cmpk_gt_u32 s54, 0x43f
	v_lshl_add_u32 v144, v1, 10, v2
	s_cbranch_scc1 .LBB0_1231
	s_add_i32 m0, s88, 0
	s_nop 0
	global_load_lds_dwordx4 v144, s[50:51]

.LBB0_1285:
	s_and_b64 vcc, exec, s[6:7]
	s_cbranch_vccz .LBB0_1221
	s_and_b32 s6, s84, 0xffff
	s_mul_i32 s6, s6, 0xaaab
	s_lshr_b32 s7, s6, 21
	s_mul_i32 s7, s7, 48
	s_sub_i32 s7, s84, s7
	s_and_b32 s84, s7, 0xff
	s_mul_i32 s8, s84, 0xab
	s_lshr_b32 s6, s6, 13
	s_bfe_u32 s10, s8, 0x5000b
	s_and_b32 s53, s6, 0xff00
	s_mul_i32 s8, s10, 12
	s_lshl_b32 s14, s10, 12
	s_sub_i32 s88, 0xf00, s53
	s_sub_i32 s7, s7, s8
	s_or_b32 s50, s14, s88
	s_and_b32 s54, s7, 0xff
	s_mul_i32 s6, s50, 0x1200
	s_add_u32 s6, s3, s6
	s_addc_u32 s7, s56, 0
	s_mul_i32 s85, s54, 0x180
	s_add_u32 s8, s6, s85
	s_addc_u32 s9, s7, 0
	s_mul_i32 s86, s10, 0x1200000
	s_add_u32 s6, s57, s86
	s_addc_u32 s7, s58, 0
	s_add_u32 s6, s6, s85
	v_readfirstlane_b32 s52, v213
	s_addc_u32 s7, s7, 0
	s_lshr_b32 s82, s52, 6
	s_lshl_b32 s24, s82, 5
	v_or_b32_e32 v240, s24, v212
	v_mov_b64_e32 v[0:1], s[8:9]
	v_mad_u64_u32 v[0:1], s[8:9], v240, s80, v[0:1]
	v_mov_b32_e32 v153, v145
	v_lshl_add_u64 v[0:1], v[0:1], 0, v[152:153]
	global_load_dwordx4 v[96:99], v[0:1], off nt
	global_load_dwordx4 v[100:103], v[0:1], off offset:32 nt
	global_load_dwordx4 v[104:107], v[0:1], off offset:64 nt
	global_load_dwordx4 v[108:111], v[0:1], off offset:96 nt
	global_load_dwordx4 v[112:115], v[0:1], off offset:128 nt
	global_load_dwordx4 v[116:119], v[0:1], off offset:160 nt
	global_load_dwordx4 v[120:123], v[0:1], off offset:192 nt
	global_load_dwordx4 v[124:127], v[0:1], off offset:224 nt
	global_load_dwordx4 v[128:131], v[0:1], off offset:256 nt
	global_load_dwordx4 v[132:135], v[0:1], off offset:288 nt
	global_load_dwordx4 v[136:139], v[0:1], off offset:320 nt
	global_load_dwordx4 v[140:143], v[0:1], off offset:352 nt
	s_lshl_b32 s51, s82, 10
	v_or_b32_e32 v0, s51, v147
	v_mul_hi_i32 v1, v0, s81
	v_lshrrev_b32_e32 v2, 31, v1
	v_ashrrev_i32_e32 v1, 7, v1
	v_add_u32_e32 v1, v1, v2
	v_mul_i32_i24_e32 v2, 0x190, v1
	v_sub_u32_e32 v2, v0, v2
	v_cmp_gt_i32_e32 vcc, s73, v2
	v_min_i32_e32 v1, 63, v1
	s_cmpk_lt_u32 s52, 0x640
	v_cndmask_b32_e32 v2, 0, v2, vcc
	s_cselect_b64 s[18:19], -1, 0
	s_cmpk_gt_u32 s52, 0x63f
	v_mad_u64_u32 v[160:161], s[8:9], v1, s80, v[2:3]
	s_cbranch_scc1 .LBB0_1288
	s_add_i32 m0, s51, 0
	s_nop 0
	global_load_lds_dwordx4 v160, s[6:7]
